# P1 rows software-pipelined (next-row loads in flight, g_mix hoisted); attention inner compute hand-rewritten: scores kept in accumulators, max3 chains, permlane swap, early K/V fragment reads
# speedup vs baseline: 1.0516x; 1.0122x over previous
.Lp1_begin:
	v_and_b32_e32 v0, 63, v0
	v_readlane_b32 s20, v254, 21
	v_readlane_b32 s16, v254, 3
	v_readlane_b32 s17, v254, 4
	v_readlane_b32 s26, v254, 13
	v_readlane_b32 s27, v254, 14
	s_ashr_i32 s53, s52, 31
	v_lshlrev_b32_e32 v1, 4, v0
	v_lshlrev_b32_e32 v2, 3, v0
	v_mov_b32_e32 v3, 0x358637bd
	s_nop 2
	global_load_dwordx4 v[10:13], v1, s[26:27]
	global_load_dwordx4 v[14:17], v1, s[26:27] offset:1024
	global_load_dwordx4 v[18:21], v1, s[26:27] offset:2048
	global_load_dwordx4 v[22:25], v1, s[26:27] offset:3072
	s_mov_b32 s21, s20
	s_lshl_b32 s0, s21, 12
	s_add_u32 s4, s16, s0
	s_addc_u32 s5, s17, 0
	s_ashr_i32 s0, s21, 12
	s_mul_i32 s0, s0, 0x6000
	s_add_u32 s6, s82, s0
	s_addc_u32 s7, s83, 0
	s_add_u32 s10, s6, 0x1000
	s_addc_u32 s11, s7, 0
	global_load_dwordx4 v[26:29], v1, s[4:5] nt
	global_load_dwordx4 v[30:33], v1, s[4:5] offset:1024 nt
	global_load_dwordx4 v[34:37], v1, s[4:5] offset:2048 nt
	global_load_dwordx4 v[38:41], v1, s[4:5] offset:3072 nt
	global_load_dwordx4 v[58:61], v1, s[6:7]
	global_load_dwordx4 v[62:65], v1, s[6:7] offset:1024
	global_load_dwordx4 v[66:69], v1, s[6:7] offset:2048
	global_load_dwordx4 v[70:73], v1, s[6:7] offset:3072
	global_load_dwordx4 v[74:77], v1, s[10:11]
	global_load_dwordx4 v[78:81], v1, s[10:11] offset:1024
	global_load_dwordx4 v[82:85], v1, s[10:11] offset:2048
	global_load_dwordx4 v[86:89], v1, s[10:11] offset:3072
.Lp1_loop:
	s_lshl_b32 s0, s21, 11
	s_add_u32 s8, s82, 0x3000000
	s_addc_u32 s9, s83, 0
	s_add_u32 s8, s8, s0
	s_addc_u32 s9, s9, 0
	s_add_i32 s22, s21, s52
	s_cmp_lt_i32 s22, 0x8000
	s_cbranch_scc0 .Lp1_last_0
	s_lshl_b32 s0, s22, 12
	s_add_u32 s4, s16, s0
	s_addc_u32 s5, s17, 0
	s_ashr_i32 s0, s22, 12
	s_mul_i32 s0, s0, 0x6000
	s_add_u32 s6, s82, s0
	s_addc_u32 s7, s83, 0
	s_add_u32 s10, s6, 0x1000
	s_addc_u32 s11, s7, 0
	global_load_dwordx4 v[42:45], v1, s[4:5] nt
	global_load_dwordx4 v[46:49], v1, s[4:5] offset:1024 nt
	global_load_dwordx4 v[50:53], v1, s[4:5] offset:2048 nt
	global_load_dwordx4 v[54:57], v1, s[4:5] offset:3072 nt
	global_load_dwordx4 v[90:93], v1, s[6:7]
	global_load_dwordx4 v[94:97], v1, s[6:7] offset:1024
	global_load_dwordx4 v[98:101], v1, s[6:7] offset:2048
	global_load_dwordx4 v[102:105], v1, s[6:7] offset:3072
	global_load_dwordx4 v[106:109], v1, s[10:11]
	global_load_dwordx4 v[110:113], v1, s[10:11] offset:1024
	global_load_dwordx4 v[114:117], v1, s[10:11] offset:2048
	global_load_dwordx4 v[118:121], v1, s[10:11] offset:3072
	s_waitcnt vmcnt(12)
	v_mul_f32_e32 v122, v26, v26
	v_fmac_f32_e32 v122, v27, v27
	v_fmac_f32_e32 v122, v28, v28
	v_fmac_f32_e32 v122, v29, v29
	v_mul_f32_e32 v123, v30, v30
	v_fmac_f32_e32 v123, v31, v31
	v_fmac_f32_e32 v123, v32, v32
	v_fmac_f32_e32 v123, v33, v33
	v_mul_f32_e32 v124, v34, v34
	v_fmac_f32_e32 v124, v35, v35
	v_fmac_f32_e32 v124, v36, v36
	v_fmac_f32_e32 v124, v37, v37
	v_mul_f32_e32 v125, v38, v38
	v_fmac_f32_e32 v125, v39, v39
	v_fmac_f32_e32 v125, v40, v40
	v_fmac_f32_e32 v125, v41, v41
	v_add_f32_e32 v122, v122, v123
	v_add_f32_e32 v124, v124, v125
	v_add_f32_e32 v122, v122, v124
	s_nop 1
	v_add_f32_dpp v122, v122, v122 quad_perm:[1,0,3,2] row_mask:0xf bank_mask:0xf bound_ctrl:1
	s_nop 1
	v_add_f32_dpp v122, v122, v122 quad_perm:[2,3,0,1] row_mask:0xf bank_mask:0xf bound_ctrl:1
	s_nop 1
	v_add_f32_dpp v122, v122, v122 row_half_mirror row_mask:0xf bank_mask:0xf bound_ctrl:1
	s_nop 1
	v_add_f32_dpp v122, v122, v122 row_mirror row_mask:0xf bank_mask:0xf bound_ctrl:1
	v_mov_b32_e32 v123, v122
	s_nop 1
	v_permlane16_swap_b32_e32 v122, v123
	v_add_f32_e32 v122, v122, v123
	v_mov_b32_e32 v123, v122
	s_nop 1
	v_permlane32_swap_b32_e32 v122, v123
	v_add_f32_e32 v122, v122, v123
	v_fmamk_f32 v122, v122, 0x3a800000, v3
	v_rsq_f32_e32 v122, v122
	s_nop 0
	v_mov_b32_e32 v123, v122
	v_pk_mul_f32 v[26:27], v[122:123], v[26:27]
	v_pk_add_f32 v[74:75], v[74:75], 1.0 op_sel_hi:[1,0]
	v_pk_mul_f32 v[26:27], v[10:11], v[26:27]
	v_pk_fma_f32 v[26:27], v[74:75], v[26:27], v[58:59]
	v_pk_mul_f32 v[28:29], v[122:123], v[28:29]
	v_pk_add_f32 v[76:77], v[76:77], 1.0 op_sel_hi:[1,0]
	v_pk_mul_f32 v[28:29], v[12:13], v[28:29]
	v_pk_fma_f32 v[28:29], v[76:77], v[28:29], v[60:61]
	v_cvt_pk_bf16_f32 v124, v26, v27
	v_cvt_pk_bf16_f32 v125, v28, v29
	global_store_dwordx2 v2, v[124:125], s[8:9]
	v_pk_mul_f32 v[30:31], v[122:123], v[30:31]
	v_pk_add_f32 v[78:79], v[78:79], 1.0 op_sel_hi:[1,0]
	v_pk_mul_f32 v[30:31], v[14:15], v[30:31]
	v_pk_fma_f32 v[30:31], v[78:79], v[30:31], v[62:63]
	v_pk_mul_f32 v[32:33], v[122:123], v[32:33]
	v_pk_add_f32 v[80:81], v[80:81], 1.0 op_sel_hi:[1,0]
	v_pk_mul_f32 v[32:33], v[16:17], v[32:33]
	v_pk_fma_f32 v[32:33], v[80:81], v[32:33], v[64:65]
	v_cvt_pk_bf16_f32 v126, v30, v31
	v_cvt_pk_bf16_f32 v127, v32, v33
	global_store_dwordx2 v2, v[126:127], s[8:9] offset:512
	v_pk_mul_f32 v[34:35], v[122:123], v[34:35]
	v_pk_add_f32 v[82:83], v[82:83], 1.0 op_sel_hi:[1,0]
	v_pk_mul_f32 v[34:35], v[18:19], v[34:35]
	v_pk_fma_f32 v[34:35], v[82:83], v[34:35], v[66:67]
	v_pk_mul_f32 v[36:37], v[122:123], v[36:37]
	v_pk_add_f32 v[84:85], v[84:85], 1.0 op_sel_hi:[1,0]
	v_pk_mul_f32 v[36:37], v[20:21], v[36:37]
	v_pk_fma_f32 v[36:37], v[84:85], v[36:37], v[68:69]
	v_cvt_pk_bf16_f32 v124, v34, v35
	v_cvt_pk_bf16_f32 v125, v36, v37
	global_store_dwordx2 v2, v[124:125], s[8:9] offset:1024
	v_pk_mul_f32 v[38:39], v[122:123], v[38:39]
	v_pk_add_f32 v[86:87], v[86:87], 1.0 op_sel_hi:[1,0]
	v_pk_mul_f32 v[38:39], v[22:23], v[38:39]
	v_pk_fma_f32 v[38:39], v[86:87], v[38:39], v[70:71]
	v_pk_mul_f32 v[40:41], v[122:123], v[40:41]
	v_pk_add_f32 v[88:89], v[88:89], 1.0 op_sel_hi:[1,0]
	v_pk_mul_f32 v[40:41], v[24:25], v[40:41]
	v_pk_fma_f32 v[40:41], v[88:89], v[40:41], v[72:73]
	v_cvt_pk_bf16_f32 v126, v38, v39
	v_cvt_pk_bf16_f32 v127, v40, v41
	global_store_dwordx2 v2, v[126:127], s[8:9] offset:1536
	s_mov_b32 s21, s22
	s_branch .Lp1_next_0
.Lp1_last_0:
	s_waitcnt vmcnt(0)
	v_mul_f32_e32 v122, v26, v26
	v_fmac_f32_e32 v122, v27, v27
	v_fmac_f32_e32 v122, v28, v28
	v_fmac_f32_e32 v122, v29, v29
	v_mul_f32_e32 v123, v30, v30
	v_fmac_f32_e32 v123, v31, v31
	v_fmac_f32_e32 v123, v32, v32
	v_fmac_f32_e32 v123, v33, v33
	v_mul_f32_e32 v124, v34, v34
	v_fmac_f32_e32 v124, v35, v35
	v_fmac_f32_e32 v124, v36, v36
	v_fmac_f32_e32 v124, v37, v37
	v_mul_f32_e32 v125, v38, v38
	v_fmac_f32_e32 v125, v39, v39
	v_fmac_f32_e32 v125, v40, v40
	v_fmac_f32_e32 v125, v41, v41
	v_add_f32_e32 v122, v122, v123
	v_add_f32_e32 v124, v124, v125
	v_add_f32_e32 v122, v122, v124
	s_nop 1
	v_add_f32_dpp v122, v122, v122 quad_perm:[1,0,3,2] row_mask:0xf bank_mask:0xf bound_ctrl:1
	s_nop 1
	v_add_f32_dpp v122, v122, v122 quad_perm:[2,3,0,1] row_mask:0xf bank_mask:0xf bound_ctrl:1
	s_nop 1
	v_add_f32_dpp v122, v122, v122 row_half_mirror row_mask:0xf bank_mask:0xf bound_ctrl:1
	s_nop 1
	v_add_f32_dpp v122, v122, v122 row_mirror row_mask:0xf bank_mask:0xf bound_ctrl:1
	v_mov_b32_e32 v123, v122
	s_nop 1
	v_permlane16_swap_b32_e32 v122, v123
	v_add_f32_e32 v122, v122, v123
	v_mov_b32_e32 v123, v122
	s_nop 1
	v_permlane32_swap_b32_e32 v122, v123
	v_add_f32_e32 v122, v122, v123
	v_fmamk_f32 v122, v122, 0x3a800000, v3
	v_rsq_f32_e32 v122, v122
	s_nop 0
	v_mov_b32_e32 v123, v122
	v_pk_mul_f32 v[26:27], v[122:123], v[26:27]
	v_pk_add_f32 v[74:75], v[74:75], 1.0 op_sel_hi:[1,0]
	v_pk_mul_f32 v[26:27], v[10:11], v[26:27]
	v_pk_fma_f32 v[26:27], v[74:75], v[26:27], v[58:59]
	v_pk_mul_f32 v[28:29], v[122:123], v[28:29]
	v_pk_add_f32 v[76:77], v[76:77], 1.0 op_sel_hi:[1,0]
	v_pk_mul_f32 v[28:29], v[12:13], v[28:29]
	v_pk_fma_f32 v[28:29], v[76:77], v[28:29], v[60:61]
	v_cvt_pk_bf16_f32 v124, v26, v27
	v_cvt_pk_bf16_f32 v125, v28, v29
	global_store_dwordx2 v2, v[124:125], s[8:9]
	v_pk_mul_f32 v[30:31], v[122:123], v[30:31]
	v_pk_add_f32 v[78:79], v[78:79], 1.0 op_sel_hi:[1,0]
	v_pk_mul_f32 v[30:31], v[14:15], v[30:31]
	v_pk_fma_f32 v[30:31], v[78:79], v[30:31], v[62:63]
	v_pk_mul_f32 v[32:33], v[122:123], v[32:33]
	v_pk_add_f32 v[80:81], v[80:81], 1.0 op_sel_hi:[1,0]
	v_pk_mul_f32 v[32:33], v[16:17], v[32:33]
	v_pk_fma_f32 v[32:33], v[80:81], v[32:33], v[64:65]
	v_cvt_pk_bf16_f32 v126, v30, v31
	v_cvt_pk_bf16_f32 v127, v32, v33
	global_store_dwordx2 v2, v[126:127], s[8:9] offset:512
	v_pk_mul_f32 v[34:35], v[122:123], v[34:35]
	v_pk_add_f32 v[82:83], v[82:83], 1.0 op_sel_hi:[1,0]
	v_pk_mul_f32 v[34:35], v[18:19], v[34:35]
	v_pk_fma_f32 v[34:35], v[82:83], v[34:35], v[66:67]
	v_pk_mul_f32 v[36:37], v[122:123], v[36:37]
	v_pk_add_f32 v[84:85], v[84:85], 1.0 op_sel_hi:[1,0]
	v_pk_mul_f32 v[36:37], v[20:21], v[36:37]
	v_pk_fma_f32 v[36:37], v[84:85], v[36:37], v[68:69]
	v_cvt_pk_bf16_f32 v124, v34, v35
	v_cvt_pk_bf16_f32 v125, v36, v37
	global_store_dwordx2 v2, v[124:125], s[8:9] offset:1024
	v_pk_mul_f32 v[38:39], v[122:123], v[38:39]
	v_pk_add_f32 v[86:87], v[86:87], 1.0 op_sel_hi:[1,0]
	v_pk_mul_f32 v[38:39], v[22:23], v[38:39]
	v_pk_fma_f32 v[38:39], v[86:87], v[38:39], v[70:71]
	v_pk_mul_f32 v[40:41], v[122:123], v[40:41]
	v_pk_add_f32 v[88:89], v[88:89], 1.0 op_sel_hi:[1,0]
	v_pk_mul_f32 v[40:41], v[24:25], v[40:41]
	v_pk_fma_f32 v[40:41], v[88:89], v[40:41], v[72:73]
	v_cvt_pk_bf16_f32 v126, v38, v39
	v_cvt_pk_bf16_f32 v127, v40, v41
	global_store_dwordx2 v2, v[126:127], s[8:9] offset:1536
	s_branch .Lp1_done
.Lp1_next_0:
	s_lshl_b32 s0, s21, 11
	s_add_u32 s8, s82, 0x3000000
	s_addc_u32 s9, s83, 0
	s_add_u32 s8, s8, s0
	s_addc_u32 s9, s9, 0
	s_add_i32 s22, s21, s52
	s_cmp_lt_i32 s22, 0x8000
	s_cbranch_scc0 .Lp1_last_1
	s_lshl_b32 s0, s22, 12
	s_add_u32 s4, s16, s0
	s_addc_u32 s5, s17, 0
	s_ashr_i32 s0, s22, 12
	s_mul_i32 s0, s0, 0x6000
	s_add_u32 s6, s82, s0
	s_addc_u32 s7, s83, 0
	s_add_u32 s10, s6, 0x1000
	s_addc_u32 s11, s7, 0
	global_load_dwordx4 v[26:29], v1, s[4:5] nt
	global_load_dwordx4 v[30:33], v1, s[4:5] offset:1024 nt
	global_load_dwordx4 v[34:37], v1, s[4:5] offset:2048 nt
	global_load_dwordx4 v[38:41], v1, s[4:5] offset:3072 nt
	global_load_dwordx4 v[58:61], v1, s[6:7]
	global_load_dwordx4 v[62:65], v1, s[6:7] offset:1024
	global_load_dwordx4 v[66:69], v1, s[6:7] offset:2048
	global_load_dwordx4 v[70:73], v1, s[6:7] offset:3072
	global_load_dwordx4 v[74:77], v1, s[10:11]
	global_load_dwordx4 v[78:81], v1, s[10:11] offset:1024
	global_load_dwordx4 v[82:85], v1, s[10:11] offset:2048
	global_load_dwordx4 v[86:89], v1, s[10:11] offset:3072
	s_waitcnt vmcnt(12)
	v_mul_f32_e32 v122, v42, v42
	v_fmac_f32_e32 v122, v43, v43
	v_fmac_f32_e32 v122, v44, v44
	v_fmac_f32_e32 v122, v45, v45
	v_mul_f32_e32 v123, v46, v46
	v_fmac_f32_e32 v123, v47, v47
	v_fmac_f32_e32 v123, v48, v48
	v_fmac_f32_e32 v123, v49, v49
	v_mul_f32_e32 v124, v50, v50
	v_fmac_f32_e32 v124, v51, v51
	v_fmac_f32_e32 v124, v52, v52
	v_fmac_f32_e32 v124, v53, v53
	v_mul_f32_e32 v125, v54, v54
	v_fmac_f32_e32 v125, v55, v55
	v_fmac_f32_e32 v125, v56, v56
	v_fmac_f32_e32 v125, v57, v57
	v_add_f32_e32 v122, v122, v123
	v_add_f32_e32 v124, v124, v125
	v_add_f32_e32 v122, v122, v124
	s_nop 1
	v_add_f32_dpp v122, v122, v122 quad_perm:[1,0,3,2] row_mask:0xf bank_mask:0xf bound_ctrl:1
	s_nop 1
	v_add_f32_dpp v122, v122, v122 quad_perm:[2,3,0,1] row_mask:0xf bank_mask:0xf bound_ctrl:1
	s_nop 1
	v_add_f32_dpp v122, v122, v122 row_half_mirror row_mask:0xf bank_mask:0xf bound_ctrl:1
	s_nop 1
	v_add_f32_dpp v122, v122, v122 row_mirror row_mask:0xf bank_mask:0xf bound_ctrl:1
	v_mov_b32_e32 v123, v122
	s_nop 1
	v_permlane16_swap_b32_e32 v122, v123
	v_add_f32_e32 v122, v122, v123
	v_mov_b32_e32 v123, v122
	s_nop 1
	v_permlane32_swap_b32_e32 v122, v123
	v_add_f32_e32 v122, v122, v123
	v_fmamk_f32 v122, v122, 0x3a800000, v3
	v_rsq_f32_e32 v122, v122
	s_nop 0
	v_mov_b32_e32 v123, v122
	v_pk_mul_f32 v[42:43], v[122:123], v[42:43]
	v_pk_add_f32 v[106:107], v[106:107], 1.0 op_sel_hi:[1,0]
	v_pk_mul_f32 v[42:43], v[10:11], v[42:43]
	v_pk_fma_f32 v[42:43], v[106:107], v[42:43], v[90:91]
	v_pk_mul_f32 v[44:45], v[122:123], v[44:45]
	v_pk_add_f32 v[108:109], v[108:109], 1.0 op_sel_hi:[1,0]
	v_pk_mul_f32 v[44:45], v[12:13], v[44:45]
	v_pk_fma_f32 v[44:45], v[108:109], v[44:45], v[92:93]
	v_cvt_pk_bf16_f32 v124, v42, v43
	v_cvt_pk_bf16_f32 v125, v44, v45
	global_store_dwordx2 v2, v[124:125], s[8:9]
	v_pk_mul_f32 v[46:47], v[122:123], v[46:47]
	v_pk_add_f32 v[110:111], v[110:111], 1.0 op_sel_hi:[1,0]
	v_pk_mul_f32 v[46:47], v[14:15], v[46:47]
	v_pk_fma_f32 v[46:47], v[110:111], v[46:47], v[94:95]
	v_pk_mul_f32 v[48:49], v[122:123], v[48:49]
	v_pk_add_f32 v[112:113], v[112:113], 1.0 op_sel_hi:[1,0]
	v_pk_mul_f32 v[48:49], v[16:17], v[48:49]
	v_pk_fma_f32 v[48:49], v[112:113], v[48:49], v[96:97]
	v_cvt_pk_bf16_f32 v126, v46, v47
	v_cvt_pk_bf16_f32 v127, v48, v49
	global_store_dwordx2 v2, v[126:127], s[8:9] offset:512
	v_pk_mul_f32 v[50:51], v[122:123], v[50:51]
	v_pk_add_f32 v[114:115], v[114:115], 1.0 op_sel_hi:[1,0]
	v_pk_mul_f32 v[50:51], v[18:19], v[50:51]
	v_pk_fma_f32 v[50:51], v[114:115], v[50:51], v[98:99]
	v_pk_mul_f32 v[52:53], v[122:123], v[52:53]
	v_pk_add_f32 v[116:117], v[116:117], 1.0 op_sel_hi:[1,0]
	v_pk_mul_f32 v[52:53], v[20:21], v[52:53]
	v_pk_fma_f32 v[52:53], v[116:117], v[52:53], v[100:101]
	v_cvt_pk_bf16_f32 v124, v50, v51
	v_cvt_pk_bf16_f32 v125, v52, v53
	global_store_dwordx2 v2, v[124:125], s[8:9] offset:1024
	v_pk_mul_f32 v[54:55], v[122:123], v[54:55]
	v_pk_add_f32 v[118:119], v[118:119], 1.0 op_sel_hi:[1,0]
	v_pk_mul_f32 v[54:55], v[22:23], v[54:55]
	v_pk_fma_f32 v[54:55], v[118:119], v[54:55], v[102:103]
	v_pk_mul_f32 v[56:57], v[122:123], v[56:57]
	v_pk_add_f32 v[120:121], v[120:121], 1.0 op_sel_hi:[1,0]
	v_pk_mul_f32 v[56:57], v[24:25], v[56:57]
	v_pk_fma_f32 v[56:57], v[120:121], v[56:57], v[104:105]
	v_cvt_pk_bf16_f32 v126, v54, v55
	v_cvt_pk_bf16_f32 v127, v56, v57
	global_store_dwordx2 v2, v[126:127], s[8:9] offset:1536
	s_mov_b32 s21, s22
	s_branch .Lp1_loop
.Lp1_last_1:
	s_waitcnt vmcnt(0)
	v_mul_f32_e32 v122, v42, v42
	v_fmac_f32_e32 v122, v43, v43
	v_fmac_f32_e32 v122, v44, v44
	v_fmac_f32_e32 v122, v45, v45
	v_mul_f32_e32 v123, v46, v46
	v_fmac_f32_e32 v123, v47, v47
	v_fmac_f32_e32 v123, v48, v48
	v_fmac_f32_e32 v123, v49, v49
	v_mul_f32_e32 v124, v50, v50
	v_fmac_f32_e32 v124, v51, v51
	v_fmac_f32_e32 v124, v52, v52
	v_fmac_f32_e32 v124, v53, v53
	v_mul_f32_e32 v125, v54, v54
	v_fmac_f32_e32 v125, v55, v55
	v_fmac_f32_e32 v125, v56, v56
	v_fmac_f32_e32 v125, v57, v57
	v_add_f32_e32 v122, v122, v123
	v_add_f32_e32 v124, v124, v125
	v_add_f32_e32 v122, v122, v124
	s_nop 1
	v_add_f32_dpp v122, v122, v122 quad_perm:[1,0,3,2] row_mask:0xf bank_mask:0xf bound_ctrl:1
	s_nop 1
	v_add_f32_dpp v122, v122, v122 quad_perm:[2,3,0,1] row_mask:0xf bank_mask:0xf bound_ctrl:1
	s_nop 1
	v_add_f32_dpp v122, v122, v122 row_half_mirror row_mask:0xf bank_mask:0xf bound_ctrl:1
	s_nop 1
	v_add_f32_dpp v122, v122, v122 row_mirror row_mask:0xf bank_mask:0xf bound_ctrl:1
	v_mov_b32_e32 v123, v122
	s_nop 1
	v_permlane16_swap_b32_e32 v122, v123
	v_add_f32_e32 v122, v122, v123
	v_mov_b32_e32 v123, v122
	s_nop 1
	v_permlane32_swap_b32_e32 v122, v123
	v_add_f32_e32 v122, v122, v123
	v_fmamk_f32 v122, v122, 0x3a800000, v3
	v_rsq_f32_e32 v122, v122
	s_nop 0
	v_mov_b32_e32 v123, v122
	v_pk_mul_f32 v[42:43], v[122:123], v[42:43]
	v_pk_add_f32 v[106:107], v[106:107], 1.0 op_sel_hi:[1,0]
	v_pk_mul_f32 v[42:43], v[10:11], v[42:43]
	v_pk_fma_f32 v[42:43], v[106:107], v[42:43], v[90:91]
	v_pk_mul_f32 v[44:45], v[122:123], v[44:45]
	v_pk_add_f32 v[108:109], v[108:109], 1.0 op_sel_hi:[1,0]
	v_pk_mul_f32 v[44:45], v[12:13], v[44:45]
	v_pk_fma_f32 v[44:45], v[108:109], v[44:45], v[92:93]
	v_cvt_pk_bf16_f32 v124, v42, v43
	v_cvt_pk_bf16_f32 v125, v44, v45
	global_store_dwordx2 v2, v[124:125], s[8:9]
	v_pk_mul_f32 v[46:47], v[122:123], v[46:47]
	v_pk_add_f32 v[110:111], v[110:111], 1.0 op_sel_hi:[1,0]
	v_pk_mul_f32 v[46:47], v[14:15], v[46:47]
	v_pk_fma_f32 v[46:47], v[110:111], v[46:47], v[94:95]
	v_pk_mul_f32 v[48:49], v[122:123], v[48:49]
	v_pk_add_f32 v[112:113], v[112:113], 1.0 op_sel_hi:[1,0]
	v_pk_mul_f32 v[48:49], v[16:17], v[48:49]
	v_pk_fma_f32 v[48:49], v[112:113], v[48:49], v[96:97]
	v_cvt_pk_bf16_f32 v126, v46, v47
	v_cvt_pk_bf16_f32 v127, v48, v49
	global_store_dwordx2 v2, v[126:127], s[8:9] offset:512
	v_pk_mul_f32 v[50:51], v[122:123], v[50:51]
	v_pk_add_f32 v[114:115], v[114:115], 1.0 op_sel_hi:[1,0]
	v_pk_mul_f32 v[50:51], v[18:19], v[50:51]
	v_pk_fma_f32 v[50:51], v[114:115], v[50:51], v[98:99]
	v_pk_mul_f32 v[52:53], v[122:123], v[52:53]
	v_pk_add_f32 v[116:117], v[116:117], 1.0 op_sel_hi:[1,0]
	v_pk_mul_f32 v[52:53], v[20:21], v[52:53]
	v_pk_fma_f32 v[52:53], v[116:117], v[52:53], v[100:101]
	v_cvt_pk_bf16_f32 v124, v50, v51
	v_cvt_pk_bf16_f32 v125, v52, v53
	global_store_dwordx2 v2, v[124:125], s[8:9] offset:1024
	v_pk_mul_f32 v[54:55], v[122:123], v[54:55]
	v_pk_add_f32 v[118:119], v[118:119], 1.0 op_sel_hi:[1,0]
	v_pk_mul_f32 v[54:55], v[22:23], v[54:55]
	v_pk_fma_f32 v[54:55], v[118:119], v[54:55], v[102:103]
	v_pk_mul_f32 v[56:57], v[122:123], v[56:57]
	v_pk_add_f32 v[120:121], v[120:121], 1.0 op_sel_hi:[1,0]
	v_pk_mul_f32 v[56:57], v[24:25], v[56:57]
	v_pk_fma_f32 v[56:57], v[120:121], v[56:57], v[104:105]
	v_cvt_pk_bf16_f32 v126, v54, v55
	v_cvt_pk_bf16_f32 v127, v56, v57
	global_store_dwordx2 v2, v[126:127], s[8:9] offset:1536
	s_branch .Lp1_done
.Lp1_done:
.LBB0_281:
	s_waitcnt vmcnt(0)
	v_writelane_b32 v254, s52, 47
	s_barrier
	s_nop 0
	v_writelane_b32 v254, s53, 48
	s_mov_b64 s[0:1], exec
	v_readlane_b32 s4, v254, 1
	v_readlane_b32 s5, v254, 2
	s_and_b64 s[4:5], s[0:1], s[4:5]
	s_mov_b64 exec, s[4:5]
	s_cbranch_execz .LBB0_333
	s_add_i32 s4, 0, 0x20200
	v_mov_b32_e32 v0, s4
	s_waitcnt vmcnt(0) expcnt(0) lgkmcnt(0)
	ds_read_b32 v2, v0
	s_add_i32 s4, 0, 0x20204
	v_mov_b32_e32 v0, s4
	ds_read_b32 v0, v0
	s_waitcnt lgkmcnt(1)
	v_cmp_ne_u32_e32 vcc, 0, v2
	s_cbranch_vccnz .LBB0_297
	v_readlane_b32 s4, v254, 0
	s_mul_i32 s33, s91, s4
	s_add_u32 s4, s82, 0x980200
	s_addc_u32 s5, s83, 0
	s_add_u32 s6, s82, 0x980400
	s_addc_u32 s7, s83, 0
	s_add_u32 s8, s82, 0x980500
	s_addc_u32 s9, s83, 0
	s_add_u32 s10, s82, 0x980600
	s_addc_u32 s11, s83, 0
	s_add_u32 s16, s82, 0x980700
	s_addc_u32 s17, s83, 0
	s_add_u32 s18, s82, 0x980800
	s_addc_u32 s19, s83, 0
	s_add_u32 s20, s82, 0x980900
	s_addc_u32 s21, s83, 0
	s_add_u32 s22, s82, 0x980a00
	s_addc_u32 s23, s83, 0
	s_add_u32 s24, s82, 0x980b00
	s_addc_u32 s25, s83, 0
	s_add_u32 s26, s82, 0x980c00
	s_addc_u32 s27, s83, 0
	s_add_u32 s28, s82, 0x980d00
	s_addc_u32 s29, s83, 0
	s_add_u32 s30, s82, 0x980e00
	s_addc_u32 s31, s83, 0
	s_add_u32 s34, s82, 0x980f00
	s_addc_u32 s35, s83, 0
	s_add_u32 s36, s82, 0x981000
	s_addc_u32 s37, s83, 0
	s_add_u32 s38, s82, 0x981100
	s_addc_u32 s39, s83, 0
	s_add_u32 s40, s82, 0x981200
	s_addc_u32 s41, s83, 0
	s_add_u32 s42, s82, 0x981300
	s_mul_i32 s33, s33, s90
	s_addc_u32 s43, s83, 0
	s_mov_b32 s51, 1
	v_mov_b32_e32 v16, 0
	s_branch .LBB0_285

.LBB0_674:
	v_mov_b32_e32 v225, 0
	v_mov_b32_e32 v226, 0x358637bd
	v_mov_b32_e32 v227, v234
	v_and_b32_e32 v2, 64, v234
	v_xor_b32_e32 v1, 32, v234
	v_add_u32_e32 v2, 64, v2
	v_cmp_lt_i32_e32 vcc, v1, v2
	v_lshlrev_b32_e32 v89, 2, v237
	s_add_i32 s81, s81, s80
	v_cndmask_b32_e32 v1, v234, v1, vcc
	v_lshlrev_b32_e32 v1, 2, v1
	ds_bpermute_b32 v2, v1, v243
	v_or_b32_e32 v88, s81, v235
	v_lshlrev_b32_e32 v224, 1, v237
	v_lshl_add_u64 v[86:87], s[82:83], 0, v[224:225]
	s_mov_b64 s[8:9], 0
	s_waitcnt lgkmcnt(0)
	v_add_f32_e32 v2, v243, v2
	v_div_scale_f32 v3, s[6:7], v2, v2, 1.0
	v_rcp_f32_e32 v4, v3
	v_readlane_b32 s73, v254, 20
	v_fma_f32 v5, -v3, v4, 1.0
	v_fmac_f32_e32 v4, v5, v4
	v_div_scale_f32 v5, vcc, 1.0, v2, 1.0
	v_mul_f32_e32 v6, v5, v4
	v_fma_f32 v7, -v3, v6, v5
	v_fmac_f32_e32 v6, v7, v4
	v_fma_f32 v3, -v3, v6, v5
	v_div_fmas_f32 v3, v3, v4, v6
	v_div_fixup_f32 v10, v3, v2, 1.0
	v_pk_mul_f32 v[80:81], v[74:75], v[10:11] op_sel_hi:[1,0]
	v_pk_mul_f32 v[84:85], v[58:59], v[10:11] op_sel_hi:[1,0]
	v_pk_mul_f32 v[2:3], v[80:81], v[80:81]
	v_pk_mul_f32 v[14:15], v[76:77], v[10:11] op_sel_hi:[1,0]
	v_pk_fma_f32 v[94:95], v[84:85], v[84:85], v[2:3]
	v_pk_mul_f32 v[74:75], v[60:61], v[10:11] op_sel_hi:[1,0]
	v_pk_mul_f32 v[2:3], v[14:15], v[14:15]
	v_pk_mul_f32 v[76:77], v[78:79], v[10:11] op_sel_hi:[1,0]
	v_pk_fma_f32 v[96:97], v[74:75], v[74:75], v[2:3]
	v_pk_mul_f32 v[82:83], v[62:63], v[10:11] op_sel_hi:[1,0]
	v_pk_mul_f32 v[2:3], v[76:77], v[76:77]
	v_pk_mul_f32 v[100:101], v[50:51], v[10:11] op_sel_hi:[1,0]
	v_pk_fma_f32 v[98:99], v[82:83], v[82:83], v[2:3]
	v_pk_mul_f32 v[102:103], v[48:49], v[10:11] op_sel_hi:[1,0]
	global_load_dwordx4 v[58:61], v89, s[4:5]
	global_load_dwordx4 v[6:9], v89, s[4:5] offset:32
	global_load_dwordx4 v[48:51], v89, s[4:5] offset:128
	global_load_dwordx4 v[2:5], v89, s[4:5] offset:160
	v_pk_mul_f32 v[70:71], v[70:71], v[10:11] op_sel_hi:[1,0]
	v_pk_mul_f32 v[104:105], v[54:55], v[10:11] op_sel_hi:[1,0]
	v_pk_mul_f32 v[12:13], v[70:71], v[70:71]
	v_pk_mul_f32 v[72:73], v[72:73], v[10:11] op_sel_hi:[1,0]
	v_pk_fma_f32 v[106:107], v[104:105], v[104:105], v[12:13]
	ds_bpermute_b32 v12, v1, v239
	v_pk_mul_f32 v[78:79], v[66:67], v[10:11] op_sel_hi:[1,0]
	v_pk_mul_f32 v[90:91], v[64:65], v[10:11] op_sel_hi:[1,0]
	v_pk_mul_f32 v[92:93], v[68:69], v[10:11] op_sel_hi:[1,0]
	v_pk_mul_f32 v[108:109], v[52:53], v[10:11] op_sel_hi:[1,0]
	v_pk_mul_f32 v[110:111], v[56:57], v[10:11] op_sel_hi:[1,0]
	v_pk_mul_f32 v[10:11], v[72:73], v[72:73]
	s_waitcnt lgkmcnt(0)
	v_add_f32_e32 v56, v239, v12
	v_pk_fma_f32 v[112:113], v[110:111], v[110:111], v[10:11]
	global_load_dwordx4 v[66:69], v89, s[4:5] offset:64
	global_load_dwordx4 v[52:55], v89, s[4:5] offset:96
	global_load_dwordx4 v[62:65], v89, s[4:5] offset:192
	global_load_dwordx4 v[10:13], v89, s[4:5] offset:224
	v_div_scale_f32 v57, s[6:7], v56, v56, 1.0
	v_rcp_f32_e32 v114, v57
	v_mov_b32_e32 v123, v78
	v_mov_b32_e32 v125, v79
	v_mov_b32_e32 v127, v90
	v_fma_f32 v89, -v57, v114, 1.0
	v_fmac_f32_e32 v114, v89, v114
	v_div_scale_f32 v89, vcc, 1.0, v56, 1.0
	v_mul_f32_e32 v115, v89, v114
	v_fma_f32 v116, -v57, v115, v89
	v_fmac_f32_e32 v115, v116, v114
	v_fma_f32 v57, -v57, v115, v89
	v_div_fmas_f32 v57, v57, v114, v115
	v_div_fixup_f32 v114, v57, v56, 1.0
	v_pk_mul_f32 v[34:35], v[34:35], v[114:115] op_sel_hi:[1,0]
	v_pk_mul_f32 v[32:33], v[32:33], v[114:115] op_sel_hi:[1,0]
	v_pk_mul_f32 v[18:19], v[18:19], v[114:115] op_sel_hi:[1,0]
	v_mov_b32_e32 v122, v34
	v_mov_b32_e32 v124, v35
	v_pk_mul_f32 v[16:17], v[16:17], v[114:115] op_sel_hi:[1,0]
	v_pk_mul_f32 v[122:123], v[122:123], v[122:123]
	v_pk_mul_f32 v[124:125], v[124:125], v[124:125]
	v_mov_b32_e32 v126, v32
	v_mov_b32_e32 v128, v33
	v_mov_b32_e32 v129, v91
	v_mov_b32_e32 v130, v18
	v_mov_b32_e32 v131, v100
	v_mov_b32_e32 v132, v19
	v_mov_b32_e32 v133, v101
	v_pk_mul_f32 v[126:127], v[126:127], v[126:127]
	v_pk_mul_f32 v[128:129], v[128:129], v[128:129]
	v_pk_fma_f32 v[122:123], v[130:131], v[130:131], v[122:123]
	v_pk_fma_f32 v[124:125], v[132:133], v[132:133], v[124:125]
	v_mov_b32_e32 v130, v16
	v_mov_b32_e32 v131, v102
	v_mov_b32_e32 v132, v17
	v_mov_b32_e32 v133, v103
	v_pk_fma_f32 v[126:127], v[130:131], v[130:131], v[126:127]
	v_pk_fma_f32 v[128:129], v[132:133], v[132:133], v[128:129]
	v_pk_mul_f32 v[36:37], v[36:37], v[114:115] op_sel_hi:[1,0]
	v_pk_add_f32 v[126:127], v[126:127], v[128:129]
	v_pk_mul_f32 v[42:43], v[42:43], v[114:115] op_sel_hi:[1,0]
	v_pk_add_f32 v[122:123], v[122:123], v[126:127]
	v_pk_mul_f32 v[20:21], v[20:21], v[114:115] op_sel_hi:[1,0]
	v_pk_add_f32 v[122:123], v[124:125], v[122:123]
	v_mov_b32_e32 v124, v36
	v_mov_b32_e32 v125, v92
	v_pk_mul_f32 v[56:57], v[26:27], v[114:115] op_sel_hi:[1,0]
	v_pk_mul_f32 v[26:27], v[42:43], v[42:43]
	v_pk_mul_f32 v[38:39], v[38:39], v[114:115] op_sel_hi:[1,0]
	v_pk_mul_f32 v[124:125], v[124:125], v[124:125]
	v_mov_b32_e32 v126, v37
	v_mov_b32_e32 v127, v93
	v_mov_b32_e32 v128, v20
	v_mov_b32_e32 v129, v108
	v_pk_fma_f32 v[116:117], v[56:57], v[56:57], v[26:27]
	v_pk_mul_f32 v[26:27], v[44:45], v[114:115] op_sel_hi:[1,0]
	v_pk_mul_f32 v[22:23], v[22:23], v[114:115] op_sel_hi:[1,0]
	v_pk_mul_f32 v[120:121], v[38:39], v[38:39]
	v_pk_mul_f32 v[126:127], v[126:127], v[126:127]
	v_mov_b32_e32 v130, v21
	v_mov_b32_e32 v131, v109
	v_pk_fma_f32 v[124:125], v[128:129], v[128:129], v[124:125]
	v_pk_mul_f32 v[28:29], v[28:29], v[114:115] op_sel_hi:[1,0]
	v_pk_mul_f32 v[44:45], v[26:27], v[26:27]
	v_pk_fma_f32 v[120:121], v[22:23], v[22:23], v[120:121]
	v_pk_fma_f32 v[126:127], v[130:131], v[130:131], v[126:127]
	v_pk_add_f32 v[122:123], v[124:125], v[122:123]
	v_pk_mul_f32 v[40:41], v[40:41], v[114:115] op_sel_hi:[1,0]
	v_pk_fma_f32 v[118:119], v[28:29], v[28:29], v[44:45]
	v_pk_mul_f32 v[44:45], v[30:31], v[114:115] op_sel_hi:[1,0]
	v_pk_mul_f32 v[30:31], v[46:47], v[114:115] op_sel_hi:[1,0]
	v_pk_add_f32 v[122:123], v[126:127], v[122:123]
	v_mov_b32_e32 v124, v120
	v_mov_b32_e32 v125, v106
	v_pk_mul_f32 v[24:25], v[24:25], v[114:115] op_sel_hi:[1,0]
	v_pk_mul_f32 v[114:115], v[40:41], v[40:41]
	v_pk_add_f32 v[122:123], v[124:125], v[122:123]
	v_mov_b32_e32 v106, v121
	v_pk_fma_f32 v[114:115], v[24:25], v[24:25], v[114:115]
	v_pk_add_f32 v[106:107], v[106:107], v[122:123]
	v_mov_b32_e32 v120, v114
	v_mov_b32_e32 v121, v112
	v_pk_add_f32 v[106:107], v[120:121], v[106:107]
	v_mov_b32_e32 v112, v115
	v_pk_add_f32 v[106:107], v[112:113], v[106:107]
	v_mov_b32_e32 v112, v116
	v_mov_b32_e32 v113, v94
	v_pk_add_f32 v[106:107], v[112:113], v[106:107]
	v_mov_b32_e32 v94, v117
	v_pk_mul_f32 v[46:47], v[30:31], v[30:31]
	v_pk_add_f32 v[94:95], v[94:95], v[106:107]
	v_mov_b32_e32 v106, v118
	v_mov_b32_e32 v107, v96
	v_pk_fma_f32 v[46:47], v[44:45], v[44:45], v[46:47]
	v_pk_add_f32 v[94:95], v[106:107], v[94:95]
	v_mov_b32_e32 v96, v119
	v_pk_add_f32 v[94:95], v[96:97], v[94:95]
	v_mov_b32_e32 v96, v46
	v_mov_b32_e32 v97, v98
	v_pk_add_f32 v[94:95], v[96:97], v[94:95]
	v_mov_b32_e32 v98, v47
	v_pk_add_f32 v[46:47], v[98:99], v[94:95]
	ds_bpermute_b32 v95, v1, v47
	ds_bpermute_b32 v94, v1, v46
	s_mov_b32 s6, 0x3c800000
	v_ashrrev_i32_e32 v89, 31, v88
	v_lshlrev_b64 v[96:97], 11, v[88:89]
	v_or_b32_e32 v88, 32, v88
	s_waitcnt lgkmcnt(0)
	v_pk_add_f32 v[46:47], v[46:47], v[94:95]
	v_ashrrev_i32_e32 v89, 31, v88
	v_pk_fma_f32 v[46:47], v[46:47], s[6:7], v[226:227] op_sel_hi:[1,0,0]
	s_mov_b32 s6, 0x800000
	v_mul_f32_e32 v1, 0x4b800000, v47
	v_cmp_gt_f32_e32 vcc, s6, v47
	v_lshlrev_b64 v[88:89], 11, v[88:89]
	v_lshl_add_u64 v[96:97], v[86:87], 0, v[96:97]
	v_cndmask_b32_e32 v1, v47, v1, vcc
	v_rsq_f32_e32 v1, v1
	v_lshl_add_u64 v[86:87], v[86:87], 0, v[88:89]
	v_mul_f32_e32 v47, 0x45800000, v1
	v_cndmask_b32_e32 v88, v1, v47, vcc
	v_pk_mul_f32 v[94:95], v[102:103], v[88:89] op_sel_hi:[1,0]
	v_pk_mul_f32 v[98:99], v[100:101], v[88:89] op_sel_hi:[1,0]
	v_pk_mul_f32 v[90:91], v[90:91], v[88:89] op_sel_hi:[1,0]
	v_pk_mul_f32 v[78:79], v[78:79], v[88:89] op_sel_hi:[1,0]
	s_waitcnt vmcnt(7)
	v_pk_mul_f32 v[94:95], v[58:59], v[94:95]
	v_pk_mul_f32 v[98:99], v[60:61], v[98:99]
	s_waitcnt vmcnt(5)
	v_pk_mul_f32 v[90:91], v[48:49], v[90:91]
	v_pk_mul_f32 v[78:79], v[50:51], v[78:79]
	v_cvt_pk_bf16_f32 v94, v94, v95
	v_cvt_pk_bf16_f32 v95, v98, v99
	v_cvt_pk_bf16_f32 v90, v90, v91
	v_cvt_pk_bf16_f32 v91, v78, v79
	global_store_dwordx2 v[96:97], v[94:95], off
	global_store_dwordx2 v[96:97], v[90:91], off offset:64
	v_pk_mul_f32 v[78:79], v[108:109], v[88:89] op_sel_hi:[1,0]
	v_pk_mul_f32 v[90:91], v[104:105], v[88:89] op_sel_hi:[1,0]
	v_pk_mul_f32 v[78:79], v[6:7], v[78:79]
	v_pk_mul_f32 v[90:91], v[8:9], v[90:91]
	v_cvt_pk_bf16_f32 v78, v78, v79
	v_cvt_pk_bf16_f32 v79, v90, v91
	v_pk_mul_f32 v[90:91], v[92:93], v[88:89] op_sel_hi:[1,0]
	v_pk_mul_f32 v[70:71], v[70:71], v[88:89] op_sel_hi:[1,0]
	s_waitcnt vmcnt(6)
	v_pk_mul_f32 v[90:91], v[2:3], v[90:91]
	v_pk_mul_f32 v[70:71], v[4:5], v[70:71]
	v_cvt_pk_bf16_f32 v90, v90, v91
	v_cvt_pk_bf16_f32 v91, v70, v71
	global_store_dwordx2 v[96:97], v[78:79], off offset:16
	global_store_dwordx2 v[96:97], v[90:91], off offset:80
	v_pk_mul_f32 v[70:71], v[110:111], v[88:89] op_sel_hi:[1,0]
	v_pk_mul_f32 v[78:79], v[84:85], v[88:89] op_sel_hi:[1,0]
	s_waitcnt vmcnt(7)
	v_pk_mul_f32 v[70:71], v[66:67], v[70:71]
	v_pk_mul_f32 v[78:79], v[68:69], v[78:79]
	v_cvt_pk_bf16_f32 v70, v70, v71
	v_cvt_pk_bf16_f32 v71, v78, v79
	v_pk_mul_f32 v[72:73], v[72:73], v[88:89] op_sel_hi:[1,0]
	v_pk_mul_f32 v[78:79], v[80:81], v[88:89] op_sel_hi:[1,0]
	s_waitcnt vmcnt(5)
	v_pk_mul_f32 v[72:73], v[62:63], v[72:73]
	v_pk_mul_f32 v[78:79], v[64:65], v[78:79]
	v_mul_f32_e32 v1, 0x4b800000, v46
	v_cmp_gt_f32_e32 vcc, s6, v46
	v_cvt_pk_bf16_f32 v72, v72, v73
	v_cvt_pk_bf16_f32 v73, v78, v79
	v_cndmask_b32_e32 v1, v46, v1, vcc
	global_store_dwordx2 v[96:97], v[70:71], off offset:32
	global_store_dwordx2 v[96:97], v[72:73], off offset:96
	v_pk_mul_f32 v[70:71], v[74:75], v[88:89] op_sel_hi:[1,0]
	v_pk_mul_f32 v[72:73], v[82:83], v[88:89] op_sel_hi:[1,0]
	v_rsq_f32_e32 v1, v1
	v_pk_mul_f32 v[70:71], v[52:53], v[70:71]
	v_pk_mul_f32 v[72:73], v[54:55], v[72:73]
	v_pk_mul_f32 v[14:15], v[14:15], v[88:89] op_sel_hi:[1,0]
	v_cvt_pk_bf16_f32 v70, v70, v71
	v_cvt_pk_bf16_f32 v71, v72, v73
	s_waitcnt vmcnt(6)
	v_pk_mul_f32 v[14:15], v[10:11], v[14:15]
	v_pk_mul_f32 v[72:73], v[76:77], v[88:89] op_sel_hi:[1,0]
	v_cvt_pk_bf16_f32 v14, v14, v15
	v_pk_mul_f32 v[72:73], v[12:13], v[72:73]
	s_nop 0
	v_cvt_pk_bf16_f32 v15, v72, v73
	global_store_dwordx2 v[96:97], v[70:71], off offset:48
	global_store_dwordx2 v[96:97], v[14:15], off offset:112
	v_mul_f32_e32 v14, 0x45800000, v1
	v_cndmask_b32_e32 v14, v1, v14, vcc
	v_pk_mul_f32 v[16:17], v[16:17], v[14:15] op_sel_hi:[1,0]
	v_pk_mul_f32 v[18:19], v[18:19], v[14:15] op_sel_hi:[1,0]
	v_pk_mul_f32 v[16:17], v[58:59], v[16:17]
	v_pk_mul_f32 v[18:19], v[60:61], v[18:19]
	v_cvt_pk_bf16_f32 v16, v16, v17
	v_cvt_pk_bf16_f32 v17, v18, v19
	v_pk_mul_f32 v[18:19], v[32:33], v[14:15] op_sel_hi:[1,0]
	v_pk_mul_f32 v[32:33], v[34:35], v[14:15] op_sel_hi:[1,0]
	v_pk_mul_f32 v[18:19], v[48:49], v[18:19]
	v_pk_mul_f32 v[32:33], v[50:51], v[32:33]
	v_cvt_pk_bf16_f32 v18, v18, v19
	v_cvt_pk_bf16_f32 v19, v32, v33
	global_store_dwordx2 v[86:87], v[16:17], off
	global_store_dwordx2 v[86:87], v[18:19], off offset:64
	v_pk_mul_f32 v[16:17], v[20:21], v[14:15] op_sel_hi:[1,0]
	s_and_b64 vcc, exec, s[92:93]
	v_pk_mul_f32 v[6:7], v[6:7], v[16:17]
	v_pk_mul_f32 v[16:17], v[22:23], v[14:15] op_sel_hi:[1,0]
	v_cvt_pk_bf16_f32 v6, v6, v7
	v_pk_mul_f32 v[8:9], v[8:9], v[16:17]
	s_nop 0
	v_cvt_pk_bf16_f32 v7, v8, v9
	v_pk_mul_f32 v[8:9], v[36:37], v[14:15] op_sel_hi:[1,0]
	s_nop 0
	v_pk_mul_f32 v[2:3], v[2:3], v[8:9]
	v_pk_mul_f32 v[8:9], v[38:39], v[14:15] op_sel_hi:[1,0]
	v_cvt_pk_bf16_f32 v2, v2, v3
	v_pk_mul_f32 v[4:5], v[4:5], v[8:9]
	s_nop 0
	v_cvt_pk_bf16_f32 v3, v4, v5
	global_store_dwordx2 v[86:87], v[6:7], off offset:16
	global_store_dwordx2 v[86:87], v[2:3], off offset:80
	v_pk_mul_f32 v[2:3], v[24:25], v[14:15] op_sel_hi:[1,0]
	v_pk_mul_f32 v[4:5], v[56:57], v[14:15] op_sel_hi:[1,0]
	v_pk_mul_f32 v[2:3], v[66:67], v[2:3]
	v_pk_mul_f32 v[4:5], v[68:69], v[4:5]
	v_cvt_pk_bf16_f32 v2, v2, v3
	v_cvt_pk_bf16_f32 v3, v4, v5
	v_pk_mul_f32 v[4:5], v[40:41], v[14:15] op_sel_hi:[1,0]
	v_pk_mul_f32 v[6:7], v[42:43], v[14:15] op_sel_hi:[1,0]
	v_pk_mul_f32 v[4:5], v[62:63], v[4:5]
	v_pk_mul_f32 v[6:7], v[64:65], v[6:7]
	v_cvt_pk_bf16_f32 v4, v4, v5
	v_cvt_pk_bf16_f32 v5, v6, v7
	global_store_dwordx2 v[86:87], v[2:3], off offset:32
	global_store_dwordx2 v[86:87], v[4:5], off offset:96
	v_pk_mul_f32 v[2:3], v[28:29], v[14:15] op_sel_hi:[1,0]
	v_pk_mul_f32 v[4:5], v[44:45], v[14:15] op_sel_hi:[1,0]
	v_pk_mul_f32 v[2:3], v[52:53], v[2:3]
	v_pk_mul_f32 v[4:5], v[54:55], v[4:5]
	v_cvt_pk_bf16_f32 v2, v2, v3
	v_cvt_pk_bf16_f32 v3, v4, v5
	v_pk_mul_f32 v[4:5], v[26:27], v[14:15] op_sel_hi:[1,0]
	v_pk_mul_f32 v[6:7], v[30:31], v[14:15] op_sel_hi:[1,0]
	v_pk_mul_f32 v[4:5], v[10:11], v[4:5]
	v_pk_mul_f32 v[6:7], v[12:13], v[6:7]
	v_cvt_pk_bf16_f32 v4, v4, v5
	v_cvt_pk_bf16_f32 v5, v6, v7
	global_store_dwordx2 v[86:87], v[2:3], off offset:48
	global_store_dwordx2 v[86:87], v[4:5], off offset:112
	s_cbranch_vccnz .LBB0_672

.LBB0_688:
	s_add_i32 s73, s95, 0
	v_add3_u32 v2, s73, v241, v224
	v_add3_u32 v1, s73, v242, v224
	ds_read_b128 v[96:99], v2
	ds_read_b128 v[246:249], v2 offset:6656
	ds_read_b128 v[250:253], v2 offset:32
	s_waitcnt lgkmcnt(2)
	v_mfma_f32_32x32x16_bf16 v[148:163], v[96:99], v[176:179], 0
	ds_read_b128 v[96:99], v2 offset:6688
	s_waitcnt lgkmcnt(2)
	v_mfma_f32_32x32x16_bf16 v[80:95], v[246:249], v[176:179], 0
	ds_read_b128 v[246:249], v2 offset:64
	s_waitcnt lgkmcnt(2)
	v_mfma_f32_32x32x16_bf16 v[148:163], v[250:253], v[180:183], v[148:163]
	ds_read_b128 v[250:253], v2 offset:6720
	s_waitcnt lgkmcnt(2)
	v_mfma_f32_32x32x16_bf16 v[80:95], v[96:99], v[180:183], v[80:95]
	ds_read_b128 v[96:99], v2 offset:96
	s_waitcnt lgkmcnt(2)
	v_mfma_f32_32x32x16_bf16 v[148:163], v[246:249], v[184:187], v[148:163]
	ds_read_b128 v[246:249], v2 offset:6752
	s_waitcnt lgkmcnt(2)
	v_mfma_f32_32x32x16_bf16 v[80:95], v[250:253], v[184:187], v[80:95]
	ds_read_b128 v[250:253], v2 offset:128
	s_waitcnt lgkmcnt(2)
	v_mfma_f32_32x32x16_bf16 v[148:163], v[96:99], v[188:191], v[148:163]
	ds_read_b128 v[96:99], v2 offset:6784
	s_waitcnt lgkmcnt(2)
	v_mfma_f32_32x32x16_bf16 v[80:95], v[246:249], v[188:191], v[80:95]
	ds_read_b128 v[246:249], v2 offset:160
	s_waitcnt lgkmcnt(2)
	v_mfma_f32_32x32x16_bf16 v[148:163], v[250:253], v[192:195], v[148:163]
	ds_read_b128 v[250:253], v2 offset:6816
	s_waitcnt lgkmcnt(2)
	v_mfma_f32_32x32x16_bf16 v[80:95], v[96:99], v[192:195], v[80:95]
	s_waitcnt lgkmcnt(1)
	v_mfma_f32_32x32x16_bf16 v[148:163], v[246:249], v[196:199], v[148:163]
	s_waitcnt lgkmcnt(0)
	v_mfma_f32_32x32x16_bf16 v[80:95], v[250:253], v[196:199], v[80:95]
	ds_read_b128 v[96:99], v2 offset:6656
	ds_read_b128 v[246:249], v2
	ds_read_b128 v[250:253], v2 offset:6688
	s_cmp_eq_u32 s74, s90
	s_cselect_b64 s[86:87], -1, 0
	s_cmp_lg_u32 s74, s90
	s_nop 9
	v_sub_f32_e32 v163, v163, v244
	v_sub_f32_e32 v162, v162, v244
	v_sub_f32_e32 v161, v161, v244
	v_sub_f32_e32 v160, v160, v244
	v_sub_f32_e32 v159, v159, v244
	v_sub_f32_e32 v158, v158, v244
	v_sub_f32_e32 v157, v157, v244
	v_sub_f32_e32 v156, v156, v244
	v_sub_f32_e32 v155, v155, v244
	v_sub_f32_e32 v154, v154, v244
	v_sub_f32_e32 v153, v153, v244
	v_sub_f32_e32 v152, v152, v244
	v_sub_f32_e32 v151, v151, v244
	v_sub_f32_e32 v150, v150, v244
	v_sub_f32_e32 v149, v149, v244
	v_sub_f32_e32 v148, v148, v244
	s_cbranch_scc1 .La_nomask0
	v_mov_b32_e32 v227, 0xff800000
	v_cndmask_b32_e64 v226, v148, v227, s[8:9]
	v_cndmask_b32_e64 v148, v226, v148, s[10:11]
	v_cndmask_b32_e64 v149, v227, v149, s[10:11]
	v_cndmask_b32_e64 v150, v150, v227, s[12:13]
	v_cndmask_b32_e64 v151, v151, v227, s[14:15]
	v_cndmask_b32_e64 v152, v152, v227, s[16:17]
	v_cndmask_b32_e64 v153, v153, v227, s[18:19]
	v_cndmask_b32_e64 v154, v154, v227, s[20:21]
	v_cndmask_b32_e64 v155, v155, v227, s[22:23]
	v_cndmask_b32_e64 v156, v156, v227, s[24:25]
	v_cndmask_b32_e64 v157, v157, v227, s[26:27]
	v_cndmask_b32_e64 v158, v158, v227, s[28:29]
	v_cndmask_b32_e64 v159, v159, v227, s[30:31]
	v_cndmask_b32_e64 v160, v160, v227, s[34:35]
	v_cndmask_b32_e64 v161, v161, v227, s[36:37]
	v_cndmask_b32_e64 v162, v162, v227, s[38:39]
	v_cndmask_b32_e64 v163, v163, v227, s[40:41]
	v_mov_b32_e32 v80, v227
	v_mov_b32_e32 v81, v227
	v_mov_b32_e32 v82, v227
	v_mov_b32_e32 v83, v227
	v_mov_b32_e32 v84, v227
	v_mov_b32_e32 v85, v227
	v_mov_b32_e32 v86, v227
	v_mov_b32_e32 v87, v227
	v_mov_b32_e32 v88, v227
	v_mov_b32_e32 v89, v227
	v_mov_b32_e32 v90, v227
	v_mov_b32_e32 v91, v227
	v_mov_b32_e32 v92, v227
	v_mov_b32_e32 v93, v227
	v_mov_b32_e32 v94, v227
	v_mov_b32_e32 v95, v227
	s_branch .La_max0

.La_max0:
	v_max3_f32 v225, v148, v150, v152
	v_max3_f32 v226, v149, v151, v153
	v_max3_f32 v225, v225, v154, v156
	v_max3_f32 v226, v226, v155, v157
	v_max3_f32 v225, v225, v158, v160
	v_max3_f32 v226, v226, v159, v161
	v_max3_f32 v225, v225, v162, v80
	v_max3_f32 v226, v226, v163, v81
	v_max3_f32 v225, v225, v82, v84
	v_max3_f32 v226, v226, v83, v85
	v_max3_f32 v225, v225, v86, v88
	v_max3_f32 v226, v226, v87, v89
	v_max3_f32 v225, v225, v90, v92
	v_max3_f32 v226, v226, v91, v93
	v_max_f32_e32 v225, v225, v94
	v_max_f32_e32 v226, v226, v95
	v_max_f32_e32 v225, v225, v226
	s_cmp_lg_u32 s90, 0
	s_cselect_b64 s[88:89], -1, 0
	v_mov_b32_e32 v226, v225
	s_cmp_eq_u32 s90, 0
	s_nop 0
	v_permlane32_swap_b32_e32 v225, v226
	v_max_f32_e32 v225, v225, v226
	s_cbranch_scc1 .La_resc0
	v_cmp_lt_f32_e32 vcc, s72, v225
	s_cbranch_vccz .La_qk1
	v_max_f32_e32 v225, v225, v225
	v_max_f32_e32 v225, 0, v225
.La_resc0:
	v_exp_f32_e64 v226, -v225
	v_add_f32_e32 v244, v244, v225
	v_sub_f32_e32 v148, v148, v225
	v_sub_f32_e32 v149, v149, v225
	v_sub_f32_e32 v150, v150, v225
	v_sub_f32_e32 v151, v151, v225
	v_sub_f32_e32 v152, v152, v225
	v_sub_f32_e32 v153, v153, v225
	v_sub_f32_e32 v154, v154, v225
	v_sub_f32_e32 v155, v155, v225
	v_sub_f32_e32 v156, v156, v225
	v_sub_f32_e32 v157, v157, v225
	v_sub_f32_e32 v158, v158, v225
	v_sub_f32_e32 v159, v159, v225
	v_sub_f32_e32 v160, v160, v225
	v_sub_f32_e32 v161, v161, v225
	v_sub_f32_e32 v162, v162, v225
	v_sub_f32_e32 v163, v163, v225
	v_sub_f32_e32 v80, v80, v225
	v_sub_f32_e32 v81, v81, v225
	v_sub_f32_e32 v82, v82, v225
	v_sub_f32_e32 v83, v83, v225
	v_sub_f32_e32 v84, v84, v225
	v_sub_f32_e32 v85, v85, v225
	v_sub_f32_e32 v86, v86, v225
	v_sub_f32_e32 v87, v87, v225
	v_sub_f32_e32 v88, v88, v225
	v_sub_f32_e32 v89, v89, v225
	v_sub_f32_e32 v90, v90, v225
	v_sub_f32_e32 v91, v91, v225
	v_sub_f32_e32 v92, v92, v225
	v_sub_f32_e32 v93, v93, v225
	v_sub_f32_e32 v94, v94, v225
	v_sub_f32_e32 v95, v95, v225
	v_mul_f32_e32 v243, v243, v226
	v_pk_mul_f32 v[48:49], v[48:49], v[226:227] op_sel_hi:[1,0]
	v_pk_mul_f32 v[50:51], v[50:51], v[226:227] op_sel_hi:[1,0]
	v_pk_mul_f32 v[52:53], v[52:53], v[226:227] op_sel_hi:[1,0]
	v_pk_mul_f32 v[54:55], v[54:55], v[226:227] op_sel_hi:[1,0]
	v_pk_mul_f32 v[56:57], v[56:57], v[226:227] op_sel_hi:[1,0]
	v_pk_mul_f32 v[58:59], v[58:59], v[226:227] op_sel_hi:[1,0]
	v_pk_mul_f32 v[60:61], v[60:61], v[226:227] op_sel_hi:[1,0]
	v_pk_mul_f32 v[62:63], v[62:63], v[226:227] op_sel_hi:[1,0]
	v_pk_mul_f32 v[64:65], v[64:65], v[226:227] op_sel_hi:[1,0]
	v_pk_mul_f32 v[66:67], v[66:67], v[226:227] op_sel_hi:[1,0]
	v_pk_mul_f32 v[68:69], v[68:69], v[226:227] op_sel_hi:[1,0]
	v_pk_mul_f32 v[70:71], v[70:71], v[226:227] op_sel_hi:[1,0]
	v_pk_mul_f32 v[72:73], v[72:73], v[226:227] op_sel_hi:[1,0]
	v_pk_mul_f32 v[74:75], v[74:75], v[226:227] op_sel_hi:[1,0]
	v_pk_mul_f32 v[76:77], v[76:77], v[226:227] op_sel_hi:[1,0]
	v_pk_mul_f32 v[78:79], v[78:79], v[226:227] op_sel_hi:[1,0]
.La_qk1:
	s_waitcnt lgkmcnt(2)
	v_mfma_f32_32x32x16_bf16 v[132:147], v[96:99], v[200:203], 0
	ds_read_b128 v[96:99], v2 offset:32
	s_waitcnt lgkmcnt(2)
	v_mfma_f32_32x32x16_bf16 v[116:131], v[246:249], v[200:203], 0
	ds_read_b128 v[246:249], v2 offset:6720
	s_waitcnt lgkmcnt(2)
	v_mfma_f32_32x32x16_bf16 v[132:147], v[250:253], v[204:207], v[132:147]
	ds_read_b128 v[250:253], v2 offset:64
	s_waitcnt lgkmcnt(2)
	v_mfma_f32_32x32x16_bf16 v[116:131], v[96:99], v[204:207], v[116:131]
	ds_read_b128 v[96:99], v2 offset:6752
	s_waitcnt lgkmcnt(2)
	v_mfma_f32_32x32x16_bf16 v[132:147], v[246:249], v[208:211], v[132:147]
	ds_read_b128 v[246:249], v2 offset:96
	s_waitcnt lgkmcnt(2)
	v_mfma_f32_32x32x16_bf16 v[116:131], v[250:253], v[208:211], v[116:131]
	ds_read_b128 v[250:253], v2 offset:6784
	s_waitcnt lgkmcnt(2)
	v_mfma_f32_32x32x16_bf16 v[132:147], v[96:99], v[212:215], v[132:147]
	ds_read_b128 v[96:99], v2 offset:128
	s_waitcnt lgkmcnt(2)
	v_mfma_f32_32x32x16_bf16 v[116:131], v[246:249], v[212:215], v[116:131]
	ds_read_b128 v[246:249], v2 offset:6816
	s_waitcnt lgkmcnt(2)
	v_mfma_f32_32x32x16_bf16 v[132:147], v[250:253], v[216:219], v[132:147]
	ds_read_b128 v[250:253], v2 offset:160
	s_waitcnt lgkmcnt(2)
	v_mfma_f32_32x32x16_bf16 v[116:131], v[96:99], v[216:219], v[116:131]
	s_waitcnt lgkmcnt(1)
	v_mfma_f32_32x32x16_bf16 v[132:147], v[246:249], v[220:223], v[132:147]
	s_waitcnt lgkmcnt(0)
	v_mfma_f32_32x32x16_bf16 v[116:131], v[250:253], v[220:223], v[116:131]
	ds_read_b128 v[96:99], v1 offset:13312
	ds_read_b128 v[246:249], v1 offset:17920
	ds_read_b128 v[250:253], v1 offset:13344
	s_nop 10
	v_sub_f32_e32 v147, v147, v245
	v_sub_f32_e32 v146, v146, v245
	v_sub_f32_e32 v145, v145, v245
	v_sub_f32_e32 v144, v144, v245
	v_sub_f32_e32 v143, v143, v245
	v_sub_f32_e32 v142, v142, v245
	v_sub_f32_e32 v141, v141, v245
	v_sub_f32_e32 v140, v140, v245
	v_sub_f32_e32 v139, v139, v245
	v_sub_f32_e32 v138, v138, v245
	v_sub_f32_e32 v137, v137, v245
	v_sub_f32_e32 v136, v136, v245
	v_sub_f32_e32 v135, v135, v245
	v_sub_f32_e32 v134, v134, v245
	v_sub_f32_e32 v133, v133, v245
	v_sub_f32_e32 v132, v132, v245
	s_andn2_b64 vcc, exec, s[86:87]
	s_cbranch_vccnz .La_nomask1
	v_mov_b32_e32 v227, 0xff800000
	v_cndmask_b32_e64 v132, v132, v227, s[8:9]
	v_cndmask_b32_e64 v133, v133, v227, s[42:43]
	v_cndmask_b32_e64 v134, v134, v227, s[44:45]
	v_cndmask_b32_e64 v135, v135, v227, s[46:47]
	v_cndmask_b32_e64 v136, v136, v227, s[48:49]
	v_cndmask_b32_e64 v137, v137, v227, s[50:51]
	v_cndmask_b32_e64 v138, v138, v227, s[52:53]
	v_cndmask_b32_e64 v139, v139, v227, s[54:55]
	v_cndmask_b32_e64 v140, v140, v227, s[56:57]
	v_cndmask_b32_e64 v141, v141, v227, s[58:59]
	v_cndmask_b32_e64 v142, v142, v227, s[60:61]
	v_cndmask_b32_e64 v143, v143, v227, s[62:63]
	v_cndmask_b32_e64 v144, v144, v227, s[64:65]
	v_cndmask_b32_e64 v145, v145, v227, s[66:67]
	v_cndmask_b32_e64 v146, v146, v227, s[68:69]
	v_cndmask_b32_e64 v147, v147, v227, s[70:71]
.La_nomask1:
	v_sub_f32_e32 v116, v116, v245
	v_sub_f32_e32 v117, v117, v245
	v_sub_f32_e32 v118, v118, v245
	v_sub_f32_e32 v119, v119, v245
	v_sub_f32_e32 v120, v120, v245
	v_sub_f32_e32 v121, v121, v245
	v_sub_f32_e32 v122, v122, v245
	v_sub_f32_e32 v123, v123, v245
	v_sub_f32_e32 v124, v124, v245
	v_sub_f32_e32 v125, v125, v245
	v_sub_f32_e32 v126, v126, v245
	v_sub_f32_e32 v127, v127, v245
	v_sub_f32_e32 v128, v128, v245
	v_sub_f32_e32 v129, v129, v245
	v_sub_f32_e32 v130, v130, v245
	v_sub_f32_e32 v131, v131, v245
	v_max3_f32 v225, v116, v118, v120
	v_max3_f32 v226, v117, v119, v121
	v_max3_f32 v225, v225, v122, v124
	v_max3_f32 v226, v226, v123, v125
	v_max3_f32 v225, v225, v126, v128
	v_max3_f32 v226, v226, v127, v129
	v_max3_f32 v225, v225, v130, v132
	v_max3_f32 v226, v226, v131, v133
	v_max3_f32 v225, v225, v134, v136
	v_max3_f32 v226, v226, v135, v137
	v_max3_f32 v225, v225, v138, v140
	v_max3_f32 v226, v226, v139, v141
	v_max3_f32 v225, v225, v142, v144
	v_max3_f32 v226, v226, v143, v145
	v_max_f32_e32 v225, v225, v146
	v_max_f32_e32 v226, v226, v147
	v_max_f32_e32 v225, v225, v226
	s_andn2_b64 vcc, exec, s[88:89]
	v_mov_b32_e32 v226, v225
	s_nop 1
	v_permlane32_swap_b32_e32 v225, v226
	v_max_f32_e32 v225, v225, v226
	s_cbranch_vccnz .La_resc1
	v_cmp_lt_f32_e32 vcc, s72, v225
	s_cbranch_vccz .La_exp
	v_max_f32_e32 v225, v225, v225
	v_max_f32_e32 v225, 0, v225
.La_resc1:
	v_exp_f32_e64 v226, -v225
	v_add_f32_e32 v245, v245, v225
	v_sub_f32_e32 v116, v116, v225
	v_sub_f32_e32 v117, v117, v225
	v_sub_f32_e32 v118, v118, v225
	v_sub_f32_e32 v119, v119, v225
	v_sub_f32_e32 v120, v120, v225
	v_sub_f32_e32 v121, v121, v225
	v_sub_f32_e32 v122, v122, v225
	v_sub_f32_e32 v123, v123, v225
	v_sub_f32_e32 v124, v124, v225
	v_sub_f32_e32 v125, v125, v225
	v_sub_f32_e32 v126, v126, v225
	v_sub_f32_e32 v127, v127, v225
	v_sub_f32_e32 v128, v128, v225
	v_sub_f32_e32 v129, v129, v225
	v_sub_f32_e32 v130, v130, v225
	v_sub_f32_e32 v131, v131, v225
	v_sub_f32_e32 v132, v132, v225
	v_sub_f32_e32 v133, v133, v225
	v_sub_f32_e32 v134, v134, v225
	v_sub_f32_e32 v135, v135, v225
	v_sub_f32_e32 v136, v136, v225
	v_sub_f32_e32 v137, v137, v225
	v_sub_f32_e32 v138, v138, v225
	v_sub_f32_e32 v139, v139, v225
	v_sub_f32_e32 v140, v140, v225
	v_sub_f32_e32 v141, v141, v225
	v_sub_f32_e32 v142, v142, v225
	v_sub_f32_e32 v143, v143, v225
	v_sub_f32_e32 v144, v144, v225
	v_sub_f32_e32 v145, v145, v225
	v_sub_f32_e32 v146, v146, v225
	v_sub_f32_e32 v147, v147, v225
	v_mul_f32_e32 v239, v239, v226
	v_pk_mul_f32 v[16:17], v[16:17], v[226:227] op_sel_hi:[1,0]
	v_pk_mul_f32 v[18:19], v[18:19], v[226:227] op_sel_hi:[1,0]
	v_pk_mul_f32 v[20:21], v[20:21], v[226:227] op_sel_hi:[1,0]
	v_pk_mul_f32 v[22:23], v[22:23], v[226:227] op_sel_hi:[1,0]
	v_pk_mul_f32 v[24:25], v[24:25], v[226:227] op_sel_hi:[1,0]
	v_pk_mul_f32 v[26:27], v[26:27], v[226:227] op_sel_hi:[1,0]
	v_pk_mul_f32 v[28:29], v[28:29], v[226:227] op_sel_hi:[1,0]
	v_pk_mul_f32 v[30:31], v[30:31], v[226:227] op_sel_hi:[1,0]
	v_pk_mul_f32 v[32:33], v[32:33], v[226:227] op_sel_hi:[1,0]
	v_pk_mul_f32 v[34:35], v[34:35], v[226:227] op_sel_hi:[1,0]
	v_pk_mul_f32 v[36:37], v[36:37], v[226:227] op_sel_hi:[1,0]
	v_pk_mul_f32 v[38:39], v[38:39], v[226:227] op_sel_hi:[1,0]
	v_pk_mul_f32 v[40:41], v[40:41], v[226:227] op_sel_hi:[1,0]
	v_pk_mul_f32 v[42:43], v[42:43], v[226:227] op_sel_hi:[1,0]
	v_pk_mul_f32 v[44:45], v[44:45], v[226:227] op_sel_hi:[1,0]
	v_pk_mul_f32 v[46:47], v[46:47], v[226:227] op_sel_hi:[1,0]
.La_exp:
	v_exp_f32_e32 v148, v148
	v_exp_f32_e32 v149, v149
	v_exp_f32_e32 v150, v150
	v_exp_f32_e32 v151, v151
	v_exp_f32_e32 v152, v152
	v_exp_f32_e32 v153, v153
	v_exp_f32_e32 v154, v154
	v_exp_f32_e32 v155, v155
	v_add_f32_e32 v226, v148, v149
	v_add_f32_e32 v226, v226, v150
	v_add_f32_e32 v226, v226, v151
	v_add_f32_e32 v226, v226, v152
	v_add_f32_e32 v226, v226, v153
	v_add_f32_e32 v226, v226, v154
	v_add_f32_e32 v226, v226, v155
	v_cvt_pk_bf16_f32 v148, v148, v149
	v_cvt_pk_bf16_f32 v149, v150, v151
	v_cvt_pk_bf16_f32 v150, v152, v153
	v_cvt_pk_bf16_f32 v151, v154, v155
	s_waitcnt lgkmcnt(1)
	s_nop 0
	v_mfma_f32_32x32x16_bf16 v[48:63], v[96:99], v[148:151], v[48:63]
	v_mfma_f32_32x32x16_bf16 v[64:79], v[246:249], v[148:151], v[64:79]
	v_exp_f32_e32 v116, v116
	v_exp_f32_e32 v117, v117
	v_exp_f32_e32 v118, v118
	v_exp_f32_e32 v119, v119
	v_exp_f32_e32 v120, v120
	v_exp_f32_e32 v121, v121
	v_exp_f32_e32 v122, v122
	v_exp_f32_e32 v123, v123
	v_add_f32_e32 v227, v116, v117
	v_add_f32_e32 v227, v227, v118
	v_add_f32_e32 v227, v227, v119
	v_add_f32_e32 v227, v227, v120
	v_add_f32_e32 v227, v227, v121
	v_add_f32_e32 v227, v227, v122
	v_add_f32_e32 v227, v227, v123
	v_cvt_pk_bf16_f32 v116, v116, v117
	v_cvt_pk_bf16_f32 v117, v118, v119
	v_cvt_pk_bf16_f32 v118, v120, v121
	v_cvt_pk_bf16_f32 v119, v122, v123
	s_nop 1
	v_mfma_f32_32x32x16_bf16 v[16:31], v[96:99], v[116:119], v[16:31]
	v_mfma_f32_32x32x16_bf16 v[32:47], v[246:249], v[116:119], v[32:47]
	ds_read_b128 v[96:99], v1 offset:17952
	ds_read_b128 v[246:249], v1 offset:13376
	v_exp_f32_e32 v156, v156
	v_exp_f32_e32 v157, v157
	v_exp_f32_e32 v158, v158
	v_exp_f32_e32 v159, v159
	v_exp_f32_e32 v160, v160
	v_exp_f32_e32 v161, v161
	v_exp_f32_e32 v162, v162
	v_exp_f32_e32 v163, v163
	v_add_f32_e32 v226, v226, v156
	v_add_f32_e32 v226, v226, v157
	v_add_f32_e32 v226, v226, v158
	v_add_f32_e32 v226, v226, v159
	v_add_f32_e32 v226, v226, v160
	v_add_f32_e32 v226, v226, v161
	v_add_f32_e32 v226, v226, v162
	v_add_f32_e32 v226, v226, v163
	v_cvt_pk_bf16_f32 v156, v156, v157
	v_cvt_pk_bf16_f32 v157, v158, v159
	v_cvt_pk_bf16_f32 v158, v160, v161
	v_cvt_pk_bf16_f32 v159, v162, v163
	s_waitcnt lgkmcnt(1)
	s_nop 0
	v_mfma_f32_32x32x16_bf16 v[48:63], v[250:253], v[156:159], v[48:63]
	v_mfma_f32_32x32x16_bf16 v[64:79], v[96:99], v[156:159], v[64:79]
	v_exp_f32_e32 v124, v124
	v_exp_f32_e32 v125, v125
	v_exp_f32_e32 v126, v126
	v_exp_f32_e32 v127, v127
	v_exp_f32_e32 v128, v128
	v_exp_f32_e32 v129, v129
	v_exp_f32_e32 v130, v130
	v_exp_f32_e32 v131, v131
	v_add_f32_e32 v227, v227, v124
	v_add_f32_e32 v227, v227, v125
	v_add_f32_e32 v227, v227, v126
	v_add_f32_e32 v227, v227, v127
	v_add_f32_e32 v227, v227, v128
	v_add_f32_e32 v227, v227, v129
	v_add_f32_e32 v227, v227, v130
	v_add_f32_e32 v227, v227, v131
	v_cvt_pk_bf16_f32 v124, v124, v125
	v_cvt_pk_bf16_f32 v125, v126, v127
	v_cvt_pk_bf16_f32 v126, v128, v129
	v_cvt_pk_bf16_f32 v127, v130, v131
	s_nop 1
	v_mfma_f32_32x32x16_bf16 v[16:31], v[250:253], v[124:127], v[16:31]
	v_mfma_f32_32x32x16_bf16 v[32:47], v[96:99], v[124:127], v[32:47]
	ds_read_b128 v[250:253], v1 offset:17984
	ds_read_b128 v[96:99], v1 offset:13408
	v_exp_f32_e32 v80, v80
	v_exp_f32_e32 v81, v81
	v_exp_f32_e32 v82, v82
	v_exp_f32_e32 v83, v83
	v_exp_f32_e32 v84, v84
	v_exp_f32_e32 v85, v85
	v_exp_f32_e32 v86, v86
	v_exp_f32_e32 v87, v87
	v_add_f32_e32 v226, v226, v80
	v_add_f32_e32 v226, v226, v81
	v_add_f32_e32 v226, v226, v82
	v_add_f32_e32 v226, v226, v83
	v_add_f32_e32 v226, v226, v84
	v_add_f32_e32 v226, v226, v85
	v_add_f32_e32 v226, v226, v86
	v_add_f32_e32 v226, v226, v87
	v_cvt_pk_bf16_f32 v80, v80, v81
	v_cvt_pk_bf16_f32 v81, v82, v83
	v_cvt_pk_bf16_f32 v82, v84, v85
	v_cvt_pk_bf16_f32 v83, v86, v87
	s_waitcnt lgkmcnt(1)
	s_nop 0
	v_mfma_f32_32x32x16_bf16 v[48:63], v[246:249], v[80:83], v[48:63]
	v_mfma_f32_32x32x16_bf16 v[64:79], v[250:253], v[80:83], v[64:79]
	v_exp_f32_e32 v132, v132
	v_exp_f32_e32 v133, v133
	v_exp_f32_e32 v134, v134
	v_exp_f32_e32 v135, v135
	v_exp_f32_e32 v136, v136
	v_exp_f32_e32 v137, v137
	v_exp_f32_e32 v138, v138
	v_exp_f32_e32 v139, v139
	v_add_f32_e32 v227, v227, v132
	v_add_f32_e32 v227, v227, v133
	v_add_f32_e32 v227, v227, v134
	v_add_f32_e32 v227, v227, v135
	v_add_f32_e32 v227, v227, v136
	v_add_f32_e32 v227, v227, v137
	v_add_f32_e32 v227, v227, v138
	v_add_f32_e32 v227, v227, v139
	v_cvt_pk_bf16_f32 v132, v132, v133
	v_cvt_pk_bf16_f32 v133, v134, v135
	v_cvt_pk_bf16_f32 v134, v136, v137
	v_cvt_pk_bf16_f32 v135, v138, v139
	s_nop 1
	v_mfma_f32_32x32x16_bf16 v[16:31], v[246:249], v[132:135], v[16:31]
	v_mfma_f32_32x32x16_bf16 v[32:47], v[250:253], v[132:135], v[32:47]
	ds_read_b128 v[246:249], v1 offset:18016
	v_exp_f32_e32 v88, v88
	v_exp_f32_e32 v89, v89
	v_exp_f32_e32 v90, v90
	v_exp_f32_e32 v91, v91
	v_exp_f32_e32 v92, v92
	v_exp_f32_e32 v93, v93
	v_exp_f32_e32 v94, v94
	v_exp_f32_e32 v95, v95
	v_add_f32_e32 v226, v226, v88
	v_add_f32_e32 v226, v226, v89
	v_add_f32_e32 v226, v226, v90
	v_add_f32_e32 v226, v226, v91
	v_add_f32_e32 v226, v226, v92
	v_add_f32_e32 v226, v226, v93
	v_add_f32_e32 v226, v226, v94
	v_add_f32_e32 v226, v226, v95
	v_cvt_pk_bf16_f32 v88, v88, v89
	v_cvt_pk_bf16_f32 v89, v90, v91
	v_cvt_pk_bf16_f32 v90, v92, v93
	v_cvt_pk_bf16_f32 v91, v94, v95
	v_add_f32_e32 v243, v243, v226
	s_waitcnt lgkmcnt(0)
	s_nop 0
	v_mfma_f32_32x32x16_bf16 v[48:63], v[96:99], v[88:91], v[48:63]
	v_mfma_f32_32x32x16_bf16 v[64:79], v[246:249], v[88:91], v[64:79]
	v_exp_f32_e32 v140, v140
	v_exp_f32_e32 v141, v141
	v_exp_f32_e32 v142, v142
	v_exp_f32_e32 v143, v143
	v_exp_f32_e32 v144, v144
	v_exp_f32_e32 v145, v145
	v_exp_f32_e32 v146, v146
	v_exp_f32_e32 v147, v147
	v_add_f32_e32 v227, v227, v140
	v_add_f32_e32 v227, v227, v141
	v_add_f32_e32 v227, v227, v142
	v_add_f32_e32 v227, v227, v143
	v_add_f32_e32 v227, v227, v144
	v_add_f32_e32 v227, v227, v145
	v_add_f32_e32 v227, v227, v146
	v_add_f32_e32 v227, v227, v147
	v_cvt_pk_bf16_f32 v140, v140, v141
	v_cvt_pk_bf16_f32 v141, v142, v143
	v_cvt_pk_bf16_f32 v142, v144, v145
	v_cvt_pk_bf16_f32 v143, v146, v147
	v_add_f32_e32 v239, v239, v227
	s_nop 1
	v_mfma_f32_32x32x16_bf16 v[16:31], v[96:99], v[140:143], v[16:31]
	v_mfma_f32_32x32x16_bf16 v[32:47], v[246:249], v[140:143], v[32:47]
	s_andn2_b64 vcc, exec, s[78:79]
	s_cbranch_vccnz .LBB0_707

.LBB0_707:
	s_mov_b64 s[78:79], 0x1000
	v_lshl_add_u64 v[228:229], v[228:229], 0, s[78:79]
	v_lshl_add_u64 v[230:231], v[230:231], 0, s[76:77]
	s_cmp_lg_u32 s94, s75
	v_lshl_add_u64 v[232:233], v[232:233], 0, s[76:77]
	s_waitcnt lgkmcnt(0)
	s_barrier
	s_cbranch_scc0 .LBB0_674
	s_mov_b32 s90, s75
	s_branch .LBB0_682
.LBB0_711:
	v_readlane_b32 s0, v255, 28
	v_readlane_b32 s14, v255, 42
	v_readlane_b32 s15, v255, 43
	v_readlane_b32 s57, v255, 53
	v_readlane_b32 s2, v255, 30
	v_readlane_b32 s3, v255, 31
	v_readlane_b32 s10, v255, 38
	v_readlane_b32 s11, v255, 39
	v_readlane_b32 s12, v255, 40
	v_readlane_b32 s13, v255, 41
	s_mov_b64 s[70:71], s[14:15]
	v_readlane_b32 s60, v255, 26
	v_readlane_b32 s62, v255, 24
	v_readlane_b32 s64, v255, 21
	v_readlane_b32 s36, v254, 31
	s_cmpk_gt_i32 s57, 0xff
	s_mov_b64 s[68:69], s[12:13]
	s_mov_b64 s[58:59], s[2:3]
	s_mov_b64 s[66:67], s[10:11]
	v_readlane_b32 s61, v255, 27
	v_readlane_b32 s63, v255, 25
	v_readlane_b32 s65, v255, 22
	v_readlane_b32 s56, v255, 20
	v_readlane_b32 s88, v255, 19
	v_readlane_b32 s89, v255, 18
	v_readlane_b32 s50, v254, 45
	v_readlane_b32 s51, v254, 46
	v_mbcnt_lo_u32_b32 v0, -1, 0
	v_mbcnt_hi_u32_b32 v0, -1, v0
	v_readlane_b32 s1, v255, 29
	v_readlane_b32 s4, v255, 32
	v_readlane_b32 s5, v255, 33
	v_readlane_b32 s6, v255, 34
	v_readlane_b32 s7, v255, 35
	v_readlane_b32 s8, v255, 36
	v_readlane_b32 s9, v255, 37
	v_readlane_b32 s37, v254, 32
	v_readlane_b32 s38, v254, 33
	v_readlane_b32 s39, v254, 34
	v_readlane_b32 s40, v254, 35
	v_readlane_b32 s41, v254, 36
	v_readlane_b32 s42, v254, 37
	v_readlane_b32 s43, v254, 38
	v_readlane_b32 s44, v254, 39
	v_readlane_b32 s45, v254, 40
	v_readlane_b32 s46, v254, 41
	v_readlane_b32 s47, v254, 42
	v_readlane_b32 s48, v254, 43
	v_readlane_b32 s49, v254, 44
	s_cbranch_scc1 .LBB0_796
	v_and_b32_e32 v0, 63, v0
	v_readlane_b32 s0, v254, 19
	v_mov_b32_e32 v80, 0x700000
	v_mov_b32_e32 v81, 0x710000
	v_or_b32_e32 v78, s0, v0
	v_add_u32_e32 v79, s0, v0
	v_mov_b32_e32 v82, 0x720000
	s_mov_b64 s[2:3], 0x40000
	s_mov_b64 s[4:5], 0x1000
	s_mov_b64 s[8:9], 0x80000
	s_branch .LBB0_714
